# p2_pre work redistributed to waves 1-7 (wave 0 only runs the grid-barrier protocol), fully overlapping p2_pre with the post-P1 grid barrier
# speedup vs baseline: 1.0204x; 1.0079x over previous
.LBB0_334:
	s_mov_b64 s[12:13], s[0:1]
	s_load_dwordx2 s[8:9], s[12:13], 0x80
	s_mul_i32 s4, s19, 7
	v_and_b32_e32 v80, 63, v2
	s_add_i32 s4, s4, s16
	s_add_i32 s4, s4, -1
	s_cmp_eq_u32 s33, 0
	s_cbranch_scc1 .LBB0_366
	s_mul_i32 s6, s18, 7
	s_cmpk_gt_i32 s4, 0x67f
	v_lshlrev_b32_e32 v0, 3, v80
	s_cbranch_scc1 .LBB0_363
	v_and_b32_e32 v16, 31, v2
	v_and_b32_e32 v2, 56, v0
	v_mov_b32_e32 v3, 0
	v_mul_u32_u24_e32 v6, 0x84, v2
	v_lshlrev_b32_e32 v2, 1, v2
	s_lshl_b32 s5, s16, 14
	v_lshrrev_b32_e32 v81, 3, v80
	s_waitcnt lgkmcnt(0)
	v_lshl_add_u64 v[12:13], s[8:9], 0, v[2:3]
	s_mov_b64 s[20:21], 0x1400000
	s_add_i32 s7, s5, 0
	v_lshrrev_b32_e32 v1, 5, v80
	v_lshl_add_u64 v[4:5], v[12:13], 0, s[20:21]
	v_lshlrev_b32_e32 v2, 2, v81
	s_mov_b64 s[20:21], 0x1200000
	v_add3_u32 v82, s7, v6, v2
	v_lshl_add_u64 v[6:7], v[12:13], 0, s[20:21]
	s_mov_b64 s[20:21], 0x1000000
	v_mul_u32_u24_e32 v2, 0x84, v1
	v_lshl_add_u64 v[8:9], v[12:13], 0, s[20:21]
	s_mov_b64 s[20:21], 0xf00000
	v_or_b32_e32 v2, s5, v2
	s_lshl_b32 s5, s4, 5
	s_mov_b32 s7, 0
	s_lshl_b32 s19, s4, 1
	s_mov_b32 s16, 0
	v_lshl_add_u64 v[10:11], v[12:13], 0, s[20:21]
	s_mov_b64 s[20:21], 0xe00000
	v_lshlrev_b32_e32 v14, 2, v16
	s_add_i32 s22, s19, s16
	s_mov_b32 s17, 0
	v_or_b32_e32 v83, 8, v81
	v_or_b32_e32 v84, 16, v81
	v_or_b32_e32 v85, 24, v81
	v_lshl_add_u64 v[12:13], v[12:13], 0, s[20:21]
	v_add3_u32 v86, v2, v14, 0
	v_mov_b32_e32 v15, v3
	s_add_i32 s5, s5, s7
	s_lshl_b32 s7, s6, 5
	v_or_b32_e32 v87, 30, v1
	s_lshl_b32 s23, s6, 1
	v_or_b32_e32 v88, 28, v1
	v_or_b32_e32 v89, 26, v1
	v_or_b32_e32 v90, 24, v1
	v_or_b32_e32 v91, 22, v1
	v_or_b32_e32 v92, 20, v1
	v_or_b32_e32 v93, 18, v1
	v_or_b32_e32 v94, 16, v1
	v_or_b32_e32 v95, 14, v1
	v_or_b32_e32 v96, 12, v1
	v_or_b32_e32 v97, 10, v1
	v_or_b32_e32 v98, 8, v1
	v_or_b32_e32 v99, 6, v1
	v_or_b32_e32 v100, 4, v1
	v_or_b32_e32 v101, 2, v1
	s_add_i32 s24, s22, 0x1f800
	s_add_i32 s25, s22, 0x1fc00
	s_movk_i32 s26, 0x7fff
	s_mov_b32 s27, 0xffff0000
	v_lshlrev_b32_e32 v16, 2, v16
	s_mov_b32 s28, s4
	s_branch .LBB0_337
